# attention phase: one static s_setprio 1 for waves 4-7 (lever: static priority raise for the younger wave half)
# speedup vs baseline: 1.0089x; 1.0005x over previous
; __device__ __forceinline__ void attn_phase(const Ptrs& P, int gw, int NGW, int lane) {
;     const bf16x8* QF = (const bf16x8*)(P.ws + WS_U1); const bf16x8* KF = QF + (size_t)M * AW / 8; const v2u* GF = (const v2u*)(KF + (size_t)M * AW / 8);
;     const bf16x8* VF = (const bf16x8*)(P.ws + WS_VT); bf16* OG = (bf16*)(P.ws + WS_OG);
;     const int r = lane & 31, hh = lane >> 5;
;     for (int u = gw; u < BATCH * AH * (SEQ / 32); u += NGW) {
;         const int qt = u & 127, bhh = u >> 7, b = bhh >> 4, h = bhh & 15;
;         const size_t rowbase = (size_t)b * SEQ;
;         bf16x8 qf[4], kf[4];
;         { const bf16x8* qp = QF + (size_t)(bhh * 128 + qt) * 256 + lane;
; #pragma unroll
;           for (int ks = 0; ks < 4; ++ks) qf[ks] = qp[ks * 64]; }
;         const bf16x8* kbase = KF + (size_t)bhh * 128 * 256 + lane;
;         const bf16x8* vbase = VF + (size_t)bhh * 128 * 256 + lane;
;         bf16x8 k1[4], k2[4], vf[2][2], v1[2][2];
;         { const int q1 = qt > 0 ? qt - 1 : 0, q2 = qt > 1 ? qt - 2 : 0;
.LBB0_635:
	s_cmp_lt_i32 s56, 7
	s_cselect_b64 s[4:5], -1, 0
	s_and_b64 s[38:39], s[4:5], s[2:3]
	s_andn2_b64 vcc, exec, s[38:39]
	s_cbranch_vccnz .LBB0_642
	s_cmpk_gt_i32 s60, 0x1fff
	s_cbranch_scc1 .LBB0_642
	s_waitcnt lgkmcnt(0)
	s_bitcmp1_b32 s60, 2
	s_cbranch_scc0 .Lp6_prio_done
	s_setprio 1
.Lp6_prio_done:
	v_lshlrev_b32_e32 v185, 4, v232
	v_lshlrev_b32_e32 v233, 3, v232
	v_and_b32_e32 v234, 31, v232
	v_lshrrev_b32_e32 v235, 5, v232
	v_lshlrev_b32_e32 v236, 2, v235
	v_lshlrev_b32_e32 v238, 4, v235
	v_cmp_lt_u32_e64 s[4:5], v236, v234
	v_or_b32_e32 v237, 1, v236
	v_cmp_lt_u32_e64 s[6:7], v237, v234
	v_or_b32_e32 v237, 2, v236
	v_cmp_lt_u32_e64 s[8:9], v237, v234
	v_or_b32_e32 v237, 3, v236
	v_cmp_lt_u32_e64 s[10:11], v237, v234
	v_or_b32_e32 v237, 8, v236
	v_cmp_lt_u32_e64 s[12:13], v237, v234
	v_or_b32_e32 v237, 9, v236
	v_cmp_lt_u32_e64 s[14:15], v237, v234
	v_or_b32_e32 v237, 10, v236
	v_cmp_lt_u32_e64 s[16:17], v237, v234
	v_or_b32_e32 v237, 11, v236
	v_cmp_lt_u32_e64 s[18:19], v237, v234
	v_or_b32_e32 v237, 16, v236
	v_cmp_lt_u32_e64 s[20:21], v237, v234
	v_or_b32_e32 v237, 17, v236
	v_cmp_lt_u32_e64 s[22:23], v237, v234
	v_or_b32_e32 v237, 18, v236
	v_cmp_lt_u32_e64 s[24:25], v237, v234
	v_or_b32_e32 v237, 19, v236
	v_cmp_lt_u32_e64 s[26:27], v237, v234
	v_or_b32_e32 v237, 24, v236
	v_cmp_lt_u32_e64 s[28:29], v237, v234
	v_or_b32_e32 v237, 25, v236
	v_cmp_lt_u32_e64 s[30:31], v237, v234
	v_or_b32_e32 v237, 26, v236
	v_cmp_lt_u32_e64 s[34:35], v237, v234
	v_or_b32_e32 v237, 27, v236
	v_cmp_lt_u32_e64 s[36:37], v237, v234
	v_cmp_gt_u32_e64 s[2:3], 32, v232
	s_add_u32 s44, s54, 0x3800000
	s_addc_u32 s45, s55, 0
	s_add_u32 s46, s54, 0x5800000
	s_addc_u32 s47, s55, 0
	s_add_u32 s48, s54, 0x9c00000
	s_addc_u32 s49, s55, 0
	s_add_u32 s50, s54, 0x7800000
	s_addc_u32 s51, s55, 0
	s_add_u32 s42, s54, 0xbc00000
	s_addc_u32 s43, s55, 0
	s_mov_b32 s58, s60
	s_cmpk_lg_i32 s64, 0x100
	s_cbranch_scc1 .Lp6_nomap
	s_and_b32 s78, s33, 7
	s_lshl_b32 s78, s78, 8
	s_lshr_b32 s79, s33, 7
	s_lshl_b32 s79, s79, 7
	s_or_b32 s78, s78, s79
	s_bfe_u32 s79, s33, 0x40003
	s_lshl_b32 s79, s79, 3
	s_or_b32 s78, s78, s79
	s_and_b32 s79, s60, 7
	s_or_b32 s58, s78, s79

; __device__ __forceinline__ unsigned xb_ld(unsigned* p)              { return __hip_atomic_load(p, __ATOMIC_RELAXED, __HIP_MEMORY_SCOPE_AGENT); }
; __device__ __forceinline__ void xcd_barrier_complete(unsigned* bar, unsigned x, unsigned& nloc, unsigned& nx) {
;     const unsigned G = gridDim.x * gridDim.y * gridDim.z;
;     unsigned sum, cnt, mine, sp = 0u;
;     for (;;) {
;         sum = 0u; cnt = 0u; mine = 0u;
; #pragma unroll
;         for (unsigned j = 0; j < 16; ++j) { const unsigned c = xb_ld(&bar[XB_XCNT(j)]); sum += c; cnt += (c > 0u) ? 1u : 0u; mine = (j == x) ? c : mine; }
; __device__ __forceinline__ void xcd_barrier(const XcdBarrier& b) {
;     asm volatile("s_waitcnt vmcnt(0)" ::: "memory");
;     __syncthreads();
;     if (threadIdx.x == 0) {
;         unsigned* bar = b.bar;
;         __builtin_amdgcn_s_waitcnt(0);
;         unsigned nloc = b.st[0], nx = b.st[1];
;         if (nloc == 0u) { xcd_barrier_complete(bar, b.x, nloc, nx); b.st[0] = nloc; b.st[1] = nx; }
.LBB0_642:
	s_setprio 0
	s_cmp_gt_i32 s57, 7
	s_cselect_b64 s[2:3], -1, 0
	s_and_b64 s[4:5], s[38:39], s[2:3]
	s_andn2_b64 vcc, exec, s[4:5]
	s_cbranch_vccnz .LBB0_696
	s_waitcnt vmcnt(0)
	s_waitcnt lgkmcnt(0)
	s_barrier
	s_and_saveexec_b64 s[4:5], s[0:1]
	s_cbranch_execz .LBB0_695
	s_add_i32 s6, 0, 0x20000
	v_mov_b32_e32 v0, s6
	s_waitcnt vmcnt(0) expcnt(0) lgkmcnt(0)
	ds_read_b32 v2, v0
	s_add_i32 s6, 0, 0x20004
	v_mov_b32_e32 v0, s6
	ds_read_b32 v0, v0
	s_waitcnt lgkmcnt(1)
	v_cmp_ne_u32_e32 vcc, 0, v2
	s_cbranch_vccnz .LBB0_659
	s_add_u32 s6, s54, 0x1000
	s_addc_u32 s7, s55, 0
	s_add_u32 s8, s54, 0x1100
	s_addc_u32 s9, s55, 0
	s_add_u32 s10, s54, 0x1200
	s_addc_u32 s11, s55, 0
	s_mul_i32 s20, s65, s61
	s_add_u32 s12, s54, 0x1300
	s_mul_i32 s20, s20, s64
	s_addc_u32 s13, s55, 0
	s_mov_b32 s21, 1
	v_mov_b32_e32 v16, 0
	s_branch .LBB0_647
